# P5 gate lines touched one stage ahead (S gates at the mid hook, next unit's R gates at the final epilogue)
# speedup vs baseline: 1.0004x; 1.0004x over previous
.Lpk1350_seg3:
	s_add_i32 s59, 0, 0x18000
	s_add_i32 s61, 0, 0x1c000
	v_add_u32_e32 v180, s59, v175
	v_add_u32_e32 v181, s61, v175
	ds_read_b128 v[136:139], v180
	ds_read_b128 v[140:143], v180 offset:1024
	ds_read_b128 v[144:147], v180 offset:2048
	ds_read_b128 v[148:151], v180 offset:3072
	ds_read_b128 v[182:185], v181
	ds_read_b128 v[186:189], v181 offset:1024
	ds_read_b128 v[190:193], v181 offset:2048
	ds_read_b128 v[194:197], v181 offset:3072
	s_mov_b32 m0, s41
	v_lshl_add_u64 v[238:239], v[230:231], 0, s[14:15]
	ds_read_b128 v[198:201], v179 offset:32768
	ds_read_b128 v[202:205], v179 offset:33792
	ds_read_b128 v[206:209], v179 offset:34816
	ds_read_b128 v[210:213], v179 offset:35840
	ds_read_b128 v[214:217], v179 offset:36864
	ds_read_b128 v[218:221], v179 offset:37888
	ds_read_b128 v[222:225], v179 offset:38912
	ds_read_b128 v[226:229], v179 offset:39936
	global_load_lds_dwordx4 v[238:239], off
	v_lshl_add_u64 v[238:239], v[232:233], 0, s[14:15]
	s_mov_b32 m0, s42
	s_nop 0
	global_load_lds_dwordx4 v[238:239], off
	s_waitcnt vmcnt(8)
	s_waitcnt lgkmcnt(0)
	s_setprio 1
	s_barrier
	v_mfma_f32_16x16x32_bf16 v[124:127], v[136:139], v[198:201], v[124:127]
	v_mfma_f32_16x16x32_bf16 v[120:123], v[144:147], v[198:201], v[120:123]
	v_mfma_f32_16x16x32_bf16 v[116:119], v[136:139], v[206:209], v[116:119]
	v_mfma_f32_16x16x32_bf16 v[112:115], v[144:147], v[206:209], v[112:115]
	v_mfma_f32_16x16x32_bf16 v[104:107], v[136:139], v[214:217], v[104:107]
	v_mfma_f32_16x16x32_bf16 v[96:99], v[144:147], v[214:217], v[96:99]
	v_mfma_f32_16x16x32_bf16 v[84:87], v[136:139], v[222:225], v[84:87]
	v_mfma_f32_16x16x32_bf16 v[80:83], v[144:147], v[222:225], v[80:83]
	v_mfma_f32_16x16x32_bf16 v[124:127], v[140:143], v[202:205], v[124:127]
	v_mfma_f32_16x16x32_bf16 v[120:123], v[148:151], v[202:205], v[120:123]
	v_mfma_f32_16x16x32_bf16 v[116:119], v[140:143], v[210:213], v[116:119]
	v_mfma_f32_16x16x32_bf16 v[112:115], v[148:151], v[210:213], v[112:115]
	v_mfma_f32_16x16x32_bf16 v[104:107], v[140:143], v[218:221], v[104:107]
	v_mfma_f32_16x16x32_bf16 v[96:99], v[148:151], v[218:221], v[96:99]
	v_mfma_f32_16x16x32_bf16 v[84:87], v[140:143], v[226:229], v[84:87]
	v_mfma_f32_16x16x32_bf16 v[80:83], v[148:151], v[226:229], v[80:83]
	s_setprio 0
	s_setprio 1
	v_mfma_f32_16x16x32_bf16 v[108:111], v[182:185], v[198:201], v[108:111]
	v_mfma_f32_16x16x32_bf16 v[100:103], v[190:193], v[198:201], v[100:103]
	v_mfma_f32_16x16x32_bf16 v[92:95], v[182:185], v[206:209], v[92:95]
	v_mfma_f32_16x16x32_bf16 v[88:91], v[190:193], v[206:209], v[88:91]
	v_mfma_f32_16x16x32_bf16 v[76:79], v[182:185], v[214:217], v[76:79]
	v_mfma_f32_16x16x32_bf16 v[72:75], v[190:193], v[214:217], v[72:75]
	v_mfma_f32_16x16x32_bf16 v[68:71], v[182:185], v[222:225], v[68:71]
	v_mfma_f32_16x16x32_bf16 v[64:67], v[190:193], v[222:225], v[64:67]
	v_mfma_f32_16x16x32_bf16 v[108:111], v[186:189], v[202:205], v[108:111]
	v_mfma_f32_16x16x32_bf16 v[100:103], v[194:197], v[202:205], v[100:103]
	v_mfma_f32_16x16x32_bf16 v[92:95], v[186:189], v[210:213], v[92:95]
	v_mfma_f32_16x16x32_bf16 v[88:91], v[194:197], v[210:213], v[88:91]
	v_mfma_f32_16x16x32_bf16 v[76:79], v[186:189], v[218:221], v[76:79]
	v_mfma_f32_16x16x32_bf16 v[72:75], v[194:197], v[218:221], v[72:75]
	v_mfma_f32_16x16x32_bf16 v[68:71], v[186:189], v[226:229], v[68:71]
	v_mfma_f32_16x16x32_bf16 v[64:67], v[194:197], v[226:229], v[64:67]
	s_barrier
	s_setprio 0
	s_add_i32 s59, s59, s38
	v_lshl_add_u64 v[238:239], v[234:235], 0, s[16:17]
	s_mov_b32 m0, s59
	s_add_i32 s60, s59, 0x2000
	ds_read_b128 v[198:201], v179 offset:49152
	ds_read_b128 v[202:205], v179 offset:50176
	global_load_lds_dwordx4 v[238:239], off
	v_lshl_add_u64 v[238:239], v[236:237], 0, s[16:17]
	s_mov_b32 m0, s60
	s_add_i32 s61, s61, s38
	ds_read_b128 v[206:209], v179 offset:51200
	ds_read_b128 v[210:213], v179 offset:52224
	global_load_lds_dwordx4 v[238:239], off
	v_lshl_add_u64 v[234:235], v[234:235], 0, s[18:19]
	s_mov_b32 m0, s61
	s_add_i32 s62, s61, 0x2000
	ds_read_b128 v[214:217], v179 offset:53248
	global_load_lds_dwordx4 v[234:235], off
	v_lshl_add_u64 v[234:235], v[236:237], 0, s[18:19]
	s_mov_b32 m0, s62
	v_lshl_add_u64 v[230:231], v[230:231], 0, s[16:17]
	ds_read_b128 v[218:221], v179 offset:54272
	global_load_lds_dwordx4 v[234:235], off
	s_mov_b32 m0, s44
	ds_read_b128 v[222:225], v179 offset:55296
	global_load_lds_dwordx4 v[230:231], off
	v_lshl_add_u64 v[230:231], v[232:233], 0, s[16:17]
	s_mov_b32 m0, s45
	ds_read_b128 v[226:229], v179 offset:56320
	global_load_lds_dwordx4 v[230:231], off
	s_waitcnt vmcnt(8)
	s_waitcnt lgkmcnt(0)
	s_setprio 1
	s_barrier
;     __device__ __forceinline__ void mid(Acc& acc, const Unit& u, int wr, int wc, int fr, int fq) const { scale(acc, u, wr, wc, fr, fq, PC_GM, false); }
;     __device__ __forceinline__ void scale(Acc& acc, const Unit& u, int wr, int wc, int fr, int fq, int pc, bool store) const {
;         int row0 = u.pm * BM + wr * 64 + fr, col0 = u.pn * BM + wc * 32 + 8 * fq;
;         asm volatile("" : "+v"(row0), "+v"(col0));
;         const char* Pb = (const char*)P; char* Ob = (char*)O;
; #pragma unroll
;         for (int ai = 0; ai < 2; ++ai) {
;             u32x4 g[4][2];
; #pragma unroll
;             for (int m = 0; m < 4; ++m) {
;                 const unsigned rowoff = (unsigned)(row0 + ai * HALF + m * 16) * (unsigned)(NIN * 2) + (unsigned)col0 * 2u;
; #pragma unroll
;                 for (int bj = 0; bj < 2; ++bj) g[m][bj] = *(const u32x4*)(Pb + (rowoff + (unsigned)((pc + bj * HALF) * 2)));
; template <class Epi, class Sched, bool ALIGN_EPI>
; __device__ __forceinline__ void gemm_phase(LAS unsigned char* lds, const Gemm g, const Sched& S, const Epi& E) {
;     ...
;             for (int t = 0; t < Epi::MID_T; t += 2) PG8_KBODY(t);
;             E.mid(acc, cur, wr, wc, fr, fq);
	v_mfma_f32_16x16x32_bf16 v[60:63], v[136:139], v[198:201], v[60:63]
	v_mfma_f32_16x16x32_bf16 v[56:59], v[144:147], v[198:201], v[56:59]
	v_mfma_f32_16x16x32_bf16 v[48:51], v[136:139], v[206:209], v[48:51]
	v_mfma_f32_16x16x32_bf16 v[40:43], v[144:147], v[206:209], v[40:43]
	v_mfma_f32_16x16x32_bf16 v[32:35], v[136:139], v[214:217], v[32:35]
	v_mfma_f32_16x16x32_bf16 v[24:27], v[144:147], v[214:217], v[24:27]
	v_mfma_f32_16x16x32_bf16 v[16:19], v[136:139], v[222:225], v[16:19]
	v_mfma_f32_16x16x32_bf16 v[8:11], v[144:147], v[222:225], v[8:11]
	v_mfma_f32_16x16x32_bf16 v[60:63], v[140:143], v[202:205], v[60:63]
	v_mfma_f32_16x16x32_bf16 v[56:59], v[148:151], v[202:205], v[56:59]
	v_mfma_f32_16x16x32_bf16 v[48:51], v[140:143], v[210:213], v[48:51]
	v_mfma_f32_16x16x32_bf16 v[40:43], v[148:151], v[210:213], v[40:43]
	v_mfma_f32_16x16x32_bf16 v[32:35], v[140:143], v[218:221], v[32:35]
	v_mfma_f32_16x16x32_bf16 v[24:27], v[148:151], v[218:221], v[24:27]
	v_mfma_f32_16x16x32_bf16 v[16:19], v[140:143], v[226:229], v[16:19]
	v_mfma_f32_16x16x32_bf16 v[8:11], v[148:151], v[226:229], v[8:11]
	s_setprio 0
	s_setprio 1
	v_mfma_f32_16x16x32_bf16 v[52:55], v[182:185], v[198:201], v[52:55]
	v_mfma_f32_16x16x32_bf16 v[44:47], v[190:193], v[198:201], v[44:47]
	v_mfma_f32_16x16x32_bf16 v[36:39], v[182:185], v[206:209], v[36:39]
	v_mfma_f32_16x16x32_bf16 v[28:31], v[190:193], v[206:209], v[28:31]
	v_mfma_f32_16x16x32_bf16 v[20:23], v[182:185], v[214:217], v[20:23]
	v_mfma_f32_16x16x32_bf16 v[12:15], v[190:193], v[214:217], v[12:15]
	v_mfma_f32_16x16x32_bf16 v[4:7], v[182:185], v[222:225], v[4:7]
	v_mfma_f32_16x16x32_bf16 v[0:3], v[190:193], v[222:225], v[0:3]
	v_mfma_f32_16x16x32_bf16 v[52:55], v[186:189], v[202:205], v[52:55]
	v_mfma_f32_16x16x32_bf16 v[44:47], v[194:197], v[202:205], v[44:47]
	v_mfma_f32_16x16x32_bf16 v[36:39], v[186:189], v[210:213], v[36:39]
	v_mfma_f32_16x16x32_bf16 v[28:31], v[194:197], v[210:213], v[28:31]
	v_mfma_f32_16x16x32_bf16 v[20:23], v[186:189], v[218:221], v[20:23]
	v_mfma_f32_16x16x32_bf16 v[12:15], v[194:197], v[218:221], v[12:15]
	v_mfma_f32_16x16x32_bf16 v[4:7], v[186:189], v[226:229], v[4:7]
	v_mfma_f32_16x16x32_bf16 v[0:3], v[194:197], v[226:229], v[0:3]
	s_barrier
	s_setprio 0
	s_add_i32 s21, s21, 2
	s_add_u32 s28, s28, 0x100
	s_addc_u32 s29, s29, 0
	s_cmp_gt_u32 s21, 5
	s_cbranch_scc0 .LBB0_1350
	v_lshl_add_u32 v182, s34, 8, v174
	v_lshl_or_b32 v183, s23, 8, v176
	v_mov_b32_e32 v128, v182
	v_mov_b32_e32 v129, v183
	s_ashr_i32 s23, s22, 31
	v_mul_lo_u32 v128, v128, s52
	v_lshl_add_u32 v228, v129, 1, v128
	v_add_u32_e32 v128, 0x1200, v228
	v_add_u32_e32 v140, 0x49200, v228
	global_load_dwordx4 v[148:151], v128, s[68:69]
	global_load_dwordx4 v[144:147], v140, s[68:69]
	v_add_u32_e32 v128, 0x1300, v228
	v_add_u32_e32 v140, 0x49300, v228
	global_load_dwordx4 v[136:139], v128, s[68:69]
	v_add_u32_e32 v184, 0x6d200, v228
	global_load_dwordx4 v[140:143], v140, s[68:69]
	v_add_u32_e32 v128, 0x25200, v228
	global_load_dwordx4 v[132:135], v128, s[68:69]
	v_add_u32_e32 v128, 0x25300, v228
	global_load_dwordx4 v[128:131], v128, s[68:69]
	v_add_u32_e32 v188, 0x6d300, v228
	global_load_dwordx4 v[184:187], v184, s[68:69]
	s_nop 0
	global_load_dwordx4 v[188:191], v188, s[68:69]
	v_add_u32_e32 v192, 0x121200, v228
	v_add_u32_e32 v196, 0x121300, v228
	global_load_dwordx4 v[192:195], v192, s[68:69]
	s_nop 0
	global_load_dwordx4 v[196:199], v196, s[68:69]
	v_add_u32_e32 v241, 0x1a00, v228
	global_load_dword v242, v241, s[68:69]
	v_add_u32_e32 v243, 0x1b00, v228
	global_load_dword v242, v243, s[68:69]
	v_add_u32_e32 v241, 0x25a00, v228
	global_load_dword v242, v241, s[68:69]
	v_add_u32_e32 v243, 0x25b00, v228
	global_load_dword v242, v243, s[68:69]
	v_add_u32_e32 v241, 0x49a00, v228
	global_load_dword v242, v241, s[68:69]
	v_add_u32_e32 v243, 0x49b00, v228
	global_load_dword v242, v243, s[68:69]
	v_add_u32_e32 v241, 0x6da00, v228
	global_load_dword v242, v241, s[68:69]
	v_add_u32_e32 v243, 0x6db00, v228
	global_load_dword v242, v243, s[68:69]
	v_add_u32_e32 v241, 0x121a00, v228
	global_load_dword v242, v241, s[68:69]
	v_add_u32_e32 v243, 0x121b00, v228
	global_load_dword v242, v243, s[68:69]
	v_add_u32_e32 v241, 0x145a00, v228
	global_load_dword v242, v241, s[68:69]
	v_add_u32_e32 v243, 0x145b00, v228
	global_load_dword v242, v243, s[68:69]
	v_add_u32_e32 v241, 0x169a00, v228
	global_load_dword v242, v241, s[68:69]
	v_add_u32_e32 v243, 0x169b00, v228
	global_load_dword v242, v243, s[68:69]
	v_add_u32_e32 v241, 0x18da00, v228
	global_load_dword v242, v241, s[68:69]
	v_add_u32_e32 v243, 0x18db00, v228
	global_load_dword v242, v243, s[68:69]
	s_ashr_i32 s21, s20, 31
	s_lshl_b64 s[28:29], s[22:23], 19
	s_lshl_b64 s[30:31], s[20:21], 19
	s_add_u32 s28, s1, s28
	s_addc_u32 s29, s33, s29
	s_add_u32 s30, s36, s30
	s_addc_u32 s31, s37, s31
	s_and_b64 s[34:35], s[2:3], exec
	s_cselect_b32 s21, s29, s27
	s_cselect_b32 s23, s28, s26
	s_cselect_b32 s63, s31, s25
	s_cselect_b32 s66, s30, s24
	s_add_u32 s26, s26, 0x40480
	s_addc_u32 s27, s27, 0
	s_add_u32 s67, s24, 0x500
	s_addc_u32 s70, s25, 0
	s_mov_b32 s71, 6
	s_waitcnt vmcnt(0)
; __device__ __forceinline__ unsigned cvt_pk_bf16(float lo, float hi) { unsigned r; asm volatile("v_cvt_pk_bf16_f32 %0, %1, %2" : "=v"(r) : "v"(lo), "v"(hi)); return r; }
; __device__ __forceinline__ float bflo(unsigned w) { return __uint_as_float(w << 16); }
; __device__ __forceinline__ float bfhi(unsigned w) { return __uint_as_float(w & 0xffff0000u); }
;     __device__ __forceinline__ void scale(Acc& acc, const Unit& u, int wr, int wc, int fr, int fq, int pc, bool store) const {
;     ...
; #pragma unroll
;             for (int m = 0; m < 4; ++m) {
;                 const unsigned ooff = (unsigned)(row0 + ai * HALF + m * 16) * (unsigned)(ldo * 2) + (unsigned)col0 * 2u;
; #pragma unroll
;                 for (int bj = 0; bj < 2; ++bj) {
;                     const u32x4 gg = g[m][bj];
;                     const f32x4 s0 = (f32x4){bflo(gg.x), bfhi(gg.x), bflo(gg.y), bfhi(gg.y)}, s1 = (f32x4){bflo(gg.z), bfhi(gg.z), bflo(gg.w), bfhi(gg.w)};
;                     const f32x4 v0 = acc[ai][bj][m][0] * s0, v1 = acc[ai][bj][m][1] * s1;
;                     if (store) { u32x4 w; w.x = cvt_pk_bf16(v0[0], v0[1]); w.y = cvt_pk_bf16(v0[2], v0[3]); w.z = cvt_pk_bf16(v1[0], v1[1]); w.w = cvt_pk_bf16(v1[2], v1[3]); *(u32x4*)(Ob + (ooff + (unsigned)(bj * HALF * 2))) = w; }
;                     else { acc[ai][bj][m][0] = v0; acc[ai][bj][m][1] = v1; }
	v_lshlrev_b32_e32 v200, 16, v148
	v_and_b32_e32 v201, 0xffff0000, v148
	v_lshlrev_b32_e32 v148, 16, v149
	v_and_b32_e32 v149, 0xffff0000, v149
	v_lshlrev_b32_e32 v204, 16, v136
	v_and_b32_e32 v205, 0xffff0000, v136
	v_lshlrev_b32_e32 v206, 16, v137
	v_and_b32_e32 v207, 0xffff0000, v137
	v_lshlrev_b32_e32 v202, 16, v150
	v_and_b32_e32 v203, 0xffff0000, v150
	v_lshlrev_b32_e32 v224, 16, v130
	v_and_b32_e32 v225, 0xffff0000, v130
	v_lshlrev_b32_e32 v226, 16, v131
	v_and_b32_e32 v227, 0xffff0000, v131
	v_lshlrev_b32_e32 v150, 16, v151
	v_and_b32_e32 v151, 0xffff0000, v151
	v_lshlrev_b32_e32 v208, 16, v138
	v_and_b32_e32 v209, 0xffff0000, v138
	v_lshlrev_b32_e32 v210, 16, v139
	v_and_b32_e32 v211, 0xffff0000, v139
	v_pk_mul_f32 v[138:139], v[126:127], v[148:149]
	v_pk_mul_f32 v[136:137], v[124:125], v[200:201]
	v_pk_mul_f32 v[126:127], v[110:111], v[206:207]
	v_pk_mul_f32 v[124:125], v[108:109], v[204:205]
	v_pk_mul_f32 v[110:111], v[90:91], v[226:227]
	v_pk_mul_f32 v[108:109], v[88:89], v[224:225]
	v_lshlrev_b32_e32 v88, 16, v144
	v_and_b32_e32 v89, 0xffff0000, v144
	v_add_u32_e32 v91, 0x145200, v228
	v_lshlrev_b32_e32 v212, 16, v132
	v_and_b32_e32 v213, 0xffff0000, v132
	v_lshlrev_b32_e32 v214, 16, v133
	v_and_b32_e32 v215, 0xffff0000, v133
	v_lshlrev_b32_e32 v216, 16, v134
	v_and_b32_e32 v217, 0xffff0000, v134
	v_lshlrev_b32_e32 v218, 16, v135
	v_and_b32_e32 v219, 0xffff0000, v135
	v_lshlrev_b32_e32 v222, 16, v129
	v_and_b32_e32 v223, 0xffff0000, v129
	v_pk_mul_f32 v[134:135], v[122:123], v[150:151]
	v_pk_mul_f32 v[132:133], v[120:121], v[202:203]
	v_pk_mul_f32 v[120:121], v[100:101], v[208:209]
	v_lshlrev_b32_e32 v90, 16, v145
	global_load_dwordx4 v[148:151], v91, s[68:69]
	v_and_b32_e32 v91, 0xffff0000, v145
	v_pk_mul_f32 v[100:101], v[104:105], v[88:89]
	v_add_u32_e32 v89, 0x145300, v228
	v_pk_mul_f32 v[122:123], v[102:103], v[210:211]
	v_pk_mul_f32 v[130:131], v[118:119], v[214:215]
	v_pk_mul_f32 v[118:119], v[114:115], v[218:219]
	v_pk_mul_f32 v[114:115], v[94:95], v[222:223]
	v_lshlrev_b32_e32 v94, 16, v147
	v_and_b32_e32 v95, 0xffff0000, v147
	v_pk_mul_f32 v[102:103], v[106:107], v[90:91]
	v_lshlrev_b32_e32 v88, 16, v140
	global_load_dwordx4 v[104:107], v89, s[68:69]
	v_and_b32_e32 v89, 0xffff0000, v140
	v_lshlrev_b32_e32 v90, 16, v141
	v_and_b32_e32 v91, 0xffff0000, v141
	v_lshlrev_b32_e32 v140, 16, v143
	v_and_b32_e32 v141, 0xffff0000, v143
	v_lshlrev_b32_e32 v220, 16, v128
	v_and_b32_e32 v221, 0xffff0000, v128
	v_pk_mul_f32 v[98:99], v[98:99], v[94:95]
	v_pk_mul_f32 v[94:95], v[78:79], v[90:91]
	v_pk_mul_f32 v[90:91], v[74:75], v[140:141]
	v_add_u32_e32 v74, 0x169200, v228
	v_pk_mul_f32 v[128:129], v[116:117], v[212:213]
	v_pk_mul_f32 v[116:117], v[112:113], v[216:217]
	v_pk_mul_f32 v[112:113], v[92:93], v[220:221]
	v_lshlrev_b32_e32 v92, 16, v146
	v_and_b32_e32 v93, 0xffff0000, v146
	v_lshlrev_b32_e32 v144, 16, v142
	v_and_b32_e32 v145, 0xffff0000, v142
	global_load_dwordx4 v[140:143], v74, s[68:69]
	v_lshlrev_b32_e32 v74, 16, v185
	v_and_b32_e32 v75, 0xffff0000, v185
	v_pk_mul_f32 v[96:97], v[96:97], v[92:93]
	v_pk_mul_f32 v[92:93], v[76:77], v[88:89]
	v_pk_mul_f32 v[88:89], v[72:73], v[144:145]
	v_lshlrev_b32_e32 v72, 16, v184
	v_and_b32_e32 v73, 0xffff0000, v184
	v_lshlrev_b32_e32 v76, 16, v186
	v_and_b32_e32 v77, 0xffff0000, v186
	v_pk_mul_f32 v[86:87], v[86:87], v[74:75]
	v_add_u32_e32 v74, 0x169300, v228
	v_lshlrev_b32_e32 v78, 16, v187
	v_and_b32_e32 v79, 0xffff0000, v187
	global_load_dwordx4 v[144:147], v74, s[68:69]
	v_pk_mul_f32 v[84:85], v[84:85], v[72:73]
	v_pk_mul_f32 v[76:77], v[80:81], v[76:77]
	v_lshlrev_b32_e32 v72, 16, v188
	v_and_b32_e32 v73, 0xffff0000, v188
	v_lshlrev_b32_e32 v184, 16, v190
	v_and_b32_e32 v185, 0xffff0000, v190
	v_add_u32_e32 v80, 0x18d200, v228
	v_pk_mul_f32 v[78:79], v[82:83], v[78:79]
	v_lshlrev_b32_e32 v74, 16, v189
	v_and_b32_e32 v75, 0xffff0000, v189
	v_lshlrev_b32_e32 v186, 16, v191
	global_load_dwordx4 v[80:83], v80, s[68:69]
	v_and_b32_e32 v187, 0xffff0000, v191
	v_pk_mul_f32 v[72:73], v[68:69], v[72:73]
	v_pk_mul_f32 v[68:69], v[64:65], v[184:185]
	v_add_u32_e32 v64, 0x18d300, v228
	v_pk_mul_f32 v[74:75], v[70:71], v[74:75]
	v_pk_mul_f32 v[70:71], v[66:67], v[186:187]
	global_load_dwordx4 v[184:187], v64, s[68:69]
	v_lshlrev_b32_e32 v64, 16, v192
	v_and_b32_e32 v65, 0xffff0000, v192
	v_lshlrev_b32_e32 v66, 16, v193
	v_and_b32_e32 v67, 0xffff0000, v193
	v_lshlrev_b32_e32 v188, 16, v194
	v_and_b32_e32 v189, 0xffff0000, v194
	v_lshlrev_b32_e32 v190, 16, v195
	v_and_b32_e32 v191, 0xffff0000, v195
	v_pk_mul_f32 v[62:63], v[62:63], v[66:67]
	v_pk_mul_f32 v[60:61], v[60:61], v[64:65]
	v_pk_mul_f32 v[66:67], v[58:59], v[190:191]
	v_pk_mul_f32 v[64:65], v[56:57], v[188:189]
	v_lshlrev_b32_e32 v56, 16, v196
	v_and_b32_e32 v57, 0xffff0000, v196
	v_lshlrev_b32_e32 v58, 16, v197
	v_and_b32_e32 v59, 0xffff0000, v197
	v_lshlrev_b32_e32 v188, 16, v198
	v_and_b32_e32 v189, 0xffff0000, v198
	v_lshlrev_b32_e32 v190, 16, v199
	v_and_b32_e32 v191, 0xffff0000, v199
	v_pk_mul_f32 v[54:55], v[54:55], v[58:59]
	v_pk_mul_f32 v[52:53], v[52:53], v[56:57]
	v_pk_mul_f32 v[58:59], v[46:47], v[190:191]
	v_pk_mul_f32 v[56:57], v[44:45], v[188:189]
	s_waitcnt vmcnt(5)
; __device__ __forceinline__ unsigned cvt_pk_bf16(float lo, float hi) { unsigned r; asm volatile("v_cvt_pk_bf16_f32 %0, %1, %2" : "=v"(r) : "v"(lo), "v"(hi)); return r; }
; __device__ __forceinline__ float bflo(unsigned w) { return __uint_as_float(w << 16); }
; __device__ __forceinline__ float bfhi(unsigned w) { return __uint_as_float(w & 0xffff0000u); }
;     __device__ __forceinline__ void scale(Acc& acc, const Unit& u, int wr, int wc, int fr, int fq, int pc, bool store) const {
;     ...
; #pragma unroll
;             for (int m = 0; m < 4; ++m) {
;                 const unsigned ooff = (unsigned)(row0 + ai * HALF + m * 16) * (unsigned)(ldo * 2) + (unsigned)col0 * 2u;
; #pragma unroll
;                 for (int bj = 0; bj < 2; ++bj) {
;                     const u32x4 gg = g[m][bj];
;                     const f32x4 s0 = (f32x4){bflo(gg.x), bfhi(gg.x), bflo(gg.y), bfhi(gg.y)}, s1 = (f32x4){bflo(gg.z), bfhi(gg.z), bflo(gg.w), bfhi(gg.w)};
;                     const f32x4 v0 = acc[ai][bj][m][0] * s0, v1 = acc[ai][bj][m][1] * s1;
;                     if (store) { u32x4 w; w.x = cvt_pk_bf16(v0[0], v0[1]); w.y = cvt_pk_bf16(v0[2], v0[3]); w.z = cvt_pk_bf16(v1[0], v1[1]); w.w = cvt_pk_bf16(v1[2], v1[3]); *(u32x4*)(Ob + (ooff + (unsigned)(bj * HALF * 2))) = w; }
;                     else { acc[ai][bj][m][0] = v0; acc[ai][bj][m][1] = v1; }
	v_lshlrev_b32_e32 v44, 16, v148
	v_and_b32_e32 v45, 0xffff0000, v148
	v_lshlrev_b32_e32 v46, 16, v149
	v_and_b32_e32 v47, 0xffff0000, v149
	v_lshlrev_b32_e32 v148, 16, v150
	v_and_b32_e32 v149, 0xffff0000, v150
	v_lshlrev_b32_e32 v150, 16, v151
	v_and_b32_e32 v151, 0xffff0000, v151
	v_pk_mul_f32 v[46:47], v[50:51], v[46:47]
	v_pk_mul_f32 v[44:45], v[48:49], v[44:45]
	v_pk_mul_f32 v[50:51], v[42:43], v[150:151]
	v_pk_mul_f32 v[48:49], v[40:41], v[148:149]
	s_waitcnt vmcnt(4)
	v_lshlrev_b32_e32 v40, 16, v104
	v_and_b32_e32 v41, 0xffff0000, v104
	v_lshlrev_b32_e32 v42, 16, v105
	v_and_b32_e32 v43, 0xffff0000, v105
	v_lshlrev_b32_e32 v104, 16, v106
	v_and_b32_e32 v105, 0xffff0000, v106
	v_lshlrev_b32_e32 v106, 16, v107
	v_and_b32_e32 v107, 0xffff0000, v107
	v_pk_mul_f32 v[38:39], v[38:39], v[42:43]
	v_pk_mul_f32 v[36:37], v[36:37], v[40:41]
	v_pk_mul_f32 v[42:43], v[30:31], v[106:107]
	v_pk_mul_f32 v[40:41], v[28:29], v[104:105]
	s_waitcnt vmcnt(3)
	v_lshlrev_b32_e32 v28, 16, v140
	v_and_b32_e32 v29, 0xffff0000, v140
	v_lshlrev_b32_e32 v30, 16, v141
	v_and_b32_e32 v31, 0xffff0000, v141
	v_lshlrev_b32_e32 v104, 16, v142
	v_and_b32_e32 v105, 0xffff0000, v142
	v_lshlrev_b32_e32 v106, 16, v143
	v_and_b32_e32 v107, 0xffff0000, v143
	v_pk_mul_f32 v[30:31], v[34:35], v[30:31]
	v_pk_mul_f32 v[28:29], v[32:33], v[28:29]
	v_pk_mul_f32 v[34:35], v[26:27], v[106:107]
	v_pk_mul_f32 v[32:33], v[24:25], v[104:105]
	s_waitcnt vmcnt(2)
	v_lshlrev_b32_e32 v24, 16, v144
	v_and_b32_e32 v25, 0xffff0000, v144
	v_lshlrev_b32_e32 v26, 16, v145
	v_and_b32_e32 v27, 0xffff0000, v145
	v_lshlrev_b32_e32 v104, 16, v146
	v_and_b32_e32 v105, 0xffff0000, v146
	v_lshlrev_b32_e32 v106, 16, v147
	v_and_b32_e32 v107, 0xffff0000, v147
	v_pk_mul_f32 v[22:23], v[22:23], v[26:27]
	v_pk_mul_f32 v[20:21], v[20:21], v[24:25]
	v_pk_mul_f32 v[26:27], v[14:15], v[106:107]
	v_pk_mul_f32 v[24:25], v[12:13], v[104:105]
	s_waitcnt vmcnt(1)
	v_lshlrev_b32_e32 v12, 16, v80
	v_and_b32_e32 v13, 0xffff0000, v80
	v_lshlrev_b32_e32 v14, 16, v81
	v_and_b32_e32 v15, 0xffff0000, v81
	v_lshlrev_b32_e32 v80, 16, v82
	v_and_b32_e32 v81, 0xffff0000, v82
	v_lshlrev_b32_e32 v82, 16, v83
	v_and_b32_e32 v83, 0xffff0000, v83
	v_pk_mul_f32 v[14:15], v[18:19], v[14:15]
	v_pk_mul_f32 v[12:13], v[16:17], v[12:13]
	v_pk_mul_f32 v[10:11], v[10:11], v[82:83]
	v_pk_mul_f32 v[8:9], v[8:9], v[80:81]
	s_waitcnt vmcnt(0)
	v_lshlrev_b32_e32 v16, 16, v184
	v_and_b32_e32 v17, 0xffff0000, v184
	v_lshlrev_b32_e32 v18, 16, v185
	v_and_b32_e32 v19, 0xffff0000, v185
	v_lshlrev_b32_e32 v80, 16, v186
	v_and_b32_e32 v81, 0xffff0000, v186
	v_lshlrev_b32_e32 v82, 16, v187
	v_and_b32_e32 v83, 0xffff0000, v187
	v_pk_mul_f32 v[6:7], v[6:7], v[18:19]
	v_pk_mul_f32 v[4:5], v[4:5], v[16:17]
	v_pk_mul_f32 v[2:3], v[2:3], v[82:83]
	v_pk_mul_f32 v[0:1], v[0:1], v[80:81]

; __device__ __forceinline__ unsigned cvt_pk_bf16(float lo, float hi) { unsigned r; asm volatile("v_cvt_pk_bf16_f32 %0, %1, %2" : "=v"(r) : "v"(lo), "v"(hi)); return r; }
; __device__ __forceinline__ float bflo(unsigned w) { return __uint_as_float(w << 16); }
; __device__ __forceinline__ float bfhi(unsigned w) { return __uint_as_float(w & 0xffff0000u); }
;     __device__ __forceinline__ void scale(Acc& acc, const Unit& u, int wr, int wc, int fr, int fq, int pc, bool store) const {
;     ...
;                 const unsigned rowoff = (unsigned)(row0 + ai * HALF + m * 16) * (unsigned)(NIN * 2) + (unsigned)col0 * 2u;
; #pragma unroll
;                 for (int bj = 0; bj < 2; ++bj) g[m][bj] = *(const u32x4*)(Pb + (rowoff + (unsigned)((pc + bj * HALF) * 2)));
;             }
; #pragma unroll
;             for (int m = 0; m < 4; ++m) {
;                 const unsigned ooff = (unsigned)(row0 + ai * HALF + m * 16) * (unsigned)(ldo * 2) + (unsigned)col0 * 2u;
; #pragma unroll
;                 for (int bj = 0; bj < 2; ++bj) {
;                     const u32x4 gg = g[m][bj];
;                     const f32x4 s0 = (f32x4){bflo(gg.x), bfhi(gg.x), bflo(gg.y), bfhi(gg.y)}, s1 = (f32x4){bflo(gg.z), bfhi(gg.z), bflo(gg.w), bfhi(gg.w)};
;                     const f32x4 v0 = acc[ai][bj][m][0] * s0, v1 = acc[ai][bj][m][1] * s1;
;                     if (store) { u32x4 w; w.x = cvt_pk_bf16(v0[0], v0[1]); w.y = cvt_pk_bf16(v0[2], v0[3]); w.z = cvt_pk_bf16(v1[0], v1[1]); w.w = cvt_pk_bf16(v1[2], v1[3]); *(u32x4*)(Ob + (ooff + (unsigned)(bj * HALF * 2))) = w; }
;                     else { acc[ai][bj][m][0] = v0; acc[ai][bj][m][1] = v1; }
; template <class Epi, class Sched, bool ALIGN_EPI>
; __device__ __forceinline__ void gemm_phase(LAS unsigned char* lds, const Gemm g, const Sched& S, const Epi& E) {
;     ...
;         const bool has_next = S.next(ui + 1, nxt);
;         const char* nA = has_next ? (const char*)g.A + (size_t)nxt.pm * tstepA : cA; const char* nB = has_next ? (const char*)g.Bt + (size_t)nxt.pn * tstepB : cB;
.LBB0_1355:
	s_andn2_b64 vcc, exec, s[2:3]
	v_lshlrev_b32_e32 v16, 1, v183
	v_mad_u64_u32 v[80:81], s[24:25], v182, s52, v[16:17]
	v_add_u32_e32 v17, 0x1a00, v80
	global_load_dwordx4 v[104:107], v17, s[68:69]
	v_add_u32_e32 v17, 0x1b00, v80
	global_load_dwordx4 v[140:143], v17, s[68:69]
	v_add_u32_e32 v17, 0x25a00, v80
	global_load_dwordx4 v[144:147], v17, s[68:69]
	v_add_u32_e32 v17, 0x25b00, v80
	global_load_dwordx4 v[148:151], v17, s[68:69]
	v_add_u32_e32 v17, 0x49a00, v80
	global_load_dwordx4 v[184:187], v17, s[68:69]
	v_lshl_add_u32 v81, v182, 12, v16
	v_add_u32_e32 v16, 0x49b00, v80
	v_add_u32_e32 v17, 0x6da00, v80
	v_add_u32_e32 v18, 0x6db00, v80
	global_load_dwordx4 v[180:183], v16, s[68:69]
	global_load_dwordx4 v[188:191], v17, s[68:69]
	s_nop 0
	global_load_dwordx4 v[16:19], v18, s[68:69]
	v_add_u32_e32 v206, 0x100, v81
	v_add_u32_e32 v207, 0x10000, v81
	s_cbranch_vccnz .Lgt_skip
	v_lshl_add_u32 v240, s22, 8, v174
	v_lshl_or_b32 v243, s20, 8, v176
	v_mul_lo_u32 v240, v240, s52
	v_lshl_add_u32 v240, v243, 1, v240
	v_add_u32_e32 v241, 0x1200, v240
	global_load_dword v242, v241, s[68:69]
	v_add_u32_e32 v243, 0x1300, v240
	global_load_dword v242, v243, s[68:69]
	v_add_u32_e32 v241, 0x25200, v240
	global_load_dword v242, v241, s[68:69]
	v_add_u32_e32 v243, 0x25300, v240
	global_load_dword v242, v243, s[68:69]
	v_add_u32_e32 v241, 0x49200, v240
	global_load_dword v242, v241, s[68:69]
	v_add_u32_e32 v243, 0x49300, v240
	global_load_dword v242, v243, s[68:69]
	v_add_u32_e32 v241, 0x6d200, v240
	global_load_dword v242, v241, s[68:69]
	v_add_u32_e32 v243, 0x6d300, v240
	global_load_dword v242, v243, s[68:69]
	v_add_u32_e32 v241, 0x121200, v240
	global_load_dword v242, v241, s[68:69]
	v_add_u32_e32 v243, 0x121300, v240
	global_load_dword v242, v243, s[68:69]
	v_add_u32_e32 v241, 0x145200, v240
	global_load_dword v242, v241, s[68:69]
	v_add_u32_e32 v243, 0x145300, v240
	global_load_dword v242, v243, s[68:69]
	v_add_u32_e32 v241, 0x169200, v240
	global_load_dword v242, v241, s[68:69]
	v_add_u32_e32 v243, 0x169300, v240
	global_load_dword v242, v243, s[68:69]
	v_add_u32_e32 v241, 0x18d200, v240
	global_load_dword v242, v241, s[68:69]
	v_add_u32_e32 v243, 0x18d300, v240
	global_load_dword v242, v243, s[68:69]
.Lgt_skip:
	s_mov_b64 s[2:3], -1
	s_waitcnt vmcnt(0)
	v_lshlrev_b32_e32 v192, 16, v106
	v_and_b32_e32 v193, 0xffff0000, v106
	v_lshlrev_b32_e32 v106, 16, v107
	v_and_b32_e32 v107, 0xffff0000, v107
	v_lshlrev_b32_e32 v82, 16, v104
	v_and_b32_e32 v83, 0xffff0000, v104
	v_lshlrev_b32_e32 v104, 16, v105
	v_and_b32_e32 v105, 0xffff0000, v105
	v_pk_mul_f32 v[134:135], v[134:135], v[106:107]
	v_pk_mul_f32 v[106:107], v[132:133], v[192:193]
	v_lshlrev_b32_e32 v194, 16, v140
	v_and_b32_e32 v195, 0xffff0000, v140
	v_lshlrev_b32_e32 v140, 16, v141
	v_and_b32_e32 v141, 0xffff0000, v141
	v_lshlrev_b32_e32 v196, 16, v142
	v_and_b32_e32 v197, 0xffff0000, v142
	v_lshlrev_b32_e32 v142, 16, v143
	v_and_b32_e32 v143, 0xffff0000, v143
	v_pk_mul_f32 v[138:139], v[138:139], v[104:105]
	v_pk_mul_f32 v[82:83], v[136:137], v[82:83]
	v_lshlrev_b32_e32 v198, 16, v144
	v_cvt_pk_bf16_f32 v104, v82, v83
	v_cvt_pk_bf16_f32 v105, v138, v139
	v_cvt_pk_bf16_f32 v106, v106, v107
	v_cvt_pk_bf16_f32 v107, v134, v135
	v_and_b32_e32 v199, 0xffff0000, v144
	v_lshlrev_b32_e32 v144, 16, v145
	v_and_b32_e32 v145, 0xffff0000, v145
	v_lshlrev_b32_e32 v200, 16, v146
	v_and_b32_e32 v201, 0xffff0000, v146
	v_lshlrev_b32_e32 v146, 16, v147
	v_and_b32_e32 v147, 0xffff0000, v147
	v_pk_mul_f32 v[126:127], v[126:127], v[140:141]
	v_pk_mul_f32 v[124:125], v[124:125], v[194:195]
	v_pk_mul_f32 v[122:123], v[122:123], v[142:143]
	v_pk_mul_f32 v[120:121], v[120:121], v[196:197]
	global_store_dwordx4 v81, v[104:107], s[72:73]
	v_lshlrev_b32_e32 v202, 16, v148
	v_and_b32_e32 v203, 0xffff0000, v148
	v_cvt_pk_bf16_f32 v104, v124, v125
	v_cvt_pk_bf16_f32 v105, v126, v127
	v_cvt_pk_bf16_f32 v106, v120, v121
	v_cvt_pk_bf16_f32 v107, v122, v123
	v_lshlrev_b32_e32 v148, 16, v149
	v_and_b32_e32 v149, 0xffff0000, v149
	v_lshlrev_b32_e32 v204, 16, v150
	v_and_b32_e32 v205, 0xffff0000, v150
	v_lshlrev_b32_e32 v150, 16, v151
	v_and_b32_e32 v151, 0xffff0000, v151
	v_pk_mul_f32 v[130:131], v[130:131], v[144:145]
	v_pk_mul_f32 v[128:129], v[128:129], v[198:199]
	v_pk_mul_f32 v[118:119], v[118:119], v[146:147]
	v_pk_mul_f32 v[116:117], v[116:117], v[200:201]
	global_store_dwordx4 v206, v[104:107], s[72:73]
	v_pk_mul_f32 v[114:115], v[114:115], v[148:149]
	v_pk_mul_f32 v[112:113], v[112:113], v[202:203]
	v_cvt_pk_bf16_f32 v104, v128, v129
	v_cvt_pk_bf16_f32 v105, v130, v131
	v_cvt_pk_bf16_f32 v106, v116, v117
	v_cvt_pk_bf16_f32 v107, v118, v119
	v_pk_mul_f32 v[110:111], v[110:111], v[150:151]
	v_pk_mul_f32 v[108:109], v[108:109], v[204:205]
	global_store_dwordx4 v207, v[104:107], s[72:73]
	v_add_u32_e32 v82, 0x10100, v81
	v_and_b32_e32 v83, 0xffff0000, v184
	v_cvt_pk_bf16_f32 v104, v112, v113
	v_cvt_pk_bf16_f32 v105, v114, v115
	v_cvt_pk_bf16_f32 v106, v108, v109
	v_cvt_pk_bf16_f32 v107, v110, v111
	global_store_dwordx4 v82, v[104:107], s[72:73]
	v_lshlrev_b32_e32 v82, 16, v184
	v_lshlrev_b32_e32 v108, 16, v187
	v_lshlrev_b32_e32 v106, 16, v186
	v_and_b32_e32 v107, 0xffff0000, v186
	v_and_b32_e32 v109, 0xffff0000, v187
	v_lshlrev_b32_e32 v104, 16, v185
	v_and_b32_e32 v105, 0xffff0000, v185
	v_pk_mul_f32 v[82:83], v[100:101], v[82:83]
	v_pk_mul_f32 v[100:101], v[98:99], v[108:109]
	v_pk_mul_f32 v[98:99], v[96:97], v[106:107]
	v_add_u32_e32 v110, 0x20000, v81
	v_pk_mul_f32 v[102:103], v[102:103], v[104:105]
	v_cvt_pk_bf16_f32 v96, v82, v83
	v_lshlrev_b32_e32 v82, 16, v180
	v_cvt_pk_bf16_f32 v97, v102, v103
; __device__ __forceinline__ unsigned cvt_pk_bf16(float lo, float hi) { unsigned r; asm volatile("v_cvt_pk_bf16_f32 %0, %1, %2" : "=v"(r) : "v"(lo), "v"(hi)); return r; }
; __device__ __forceinline__ float bflo(unsigned w) { return __uint_as_float(w << 16); }
; __device__ __forceinline__ float bfhi(unsigned w) { return __uint_as_float(w & 0xffff0000u); }
;     __device__ __forceinline__ void scale(Acc& acc, const Unit& u, int wr, int wc, int fr, int fq, int pc, bool store) const {
;     ...
;                 const unsigned rowoff = (unsigned)(row0 + ai * HALF + m * 16) * (unsigned)(NIN * 2) + (unsigned)col0 * 2u;
; #pragma unroll
;                 for (int bj = 0; bj < 2; ++bj) g[m][bj] = *(const u32x4*)(Pb + (rowoff + (unsigned)((pc + bj * HALF) * 2)));
;             }
; #pragma unroll
;             for (int m = 0; m < 4; ++m) {
;                 const unsigned ooff = (unsigned)(row0 + ai * HALF + m * 16) * (unsigned)(ldo * 2) + (unsigned)col0 * 2u;
; #pragma unroll
;                 for (int bj = 0; bj < 2; ++bj) {
;                     const u32x4 gg = g[m][bj];
;                     const f32x4 s0 = (f32x4){bflo(gg.x), bfhi(gg.x), bflo(gg.y), bfhi(gg.y)}, s1 = (f32x4){bflo(gg.z), bfhi(gg.z), bflo(gg.w), bfhi(gg.w)};
;                     const f32x4 v0 = acc[ai][bj][m][0] * s0, v1 = acc[ai][bj][m][1] * s1;
;                     if (store) { u32x4 w; w.x = cvt_pk_bf16(v0[0], v0[1]); w.y = cvt_pk_bf16(v0[2], v0[3]); w.z = cvt_pk_bf16(v1[0], v1[1]); w.w = cvt_pk_bf16(v1[2], v1[3]); *(u32x4*)(Ob + (ooff + (unsigned)(bj * HALF * 2))) = w; }
;                     else { acc[ai][bj][m][0] = v0; acc[ai][bj][m][1] = v1; }
	v_cvt_pk_bf16_f32 v98, v98, v99
	v_cvt_pk_bf16_f32 v99, v100, v101
	global_store_dwordx4 v110, v[96:99], s[72:73]
	v_and_b32_e32 v83, 0xffff0000, v180
	v_lshlrev_b32_e32 v100, 16, v183
	v_lshlrev_b32_e32 v98, 16, v182
	v_and_b32_e32 v99, 0xffff0000, v182
	v_and_b32_e32 v101, 0xffff0000, v183
	v_lshlrev_b32_e32 v96, 16, v181
	v_and_b32_e32 v97, 0xffff0000, v181
	v_pk_mul_f32 v[82:83], v[92:93], v[82:83]
	v_pk_mul_f32 v[92:93], v[90:91], v[100:101]
	v_pk_mul_f32 v[90:91], v[88:89], v[98:99]
	v_pk_mul_f32 v[94:95], v[94:95], v[96:97]
	v_cvt_pk_bf16_f32 v88, v82, v83
	v_add_u32_e32 v82, 0x20100, v81
	v_cvt_pk_bf16_f32 v89, v94, v95
	v_cvt_pk_bf16_f32 v90, v90, v91
	v_cvt_pk_bf16_f32 v91, v92, v93
	global_store_dwordx4 v82, v[88:91], s[72:73]
	v_lshlrev_b32_e32 v82, 16, v188
	v_and_b32_e32 v83, 0xffff0000, v188
	v_lshlrev_b32_e32 v90, 16, v190
	v_and_b32_e32 v91, 0xffff0000, v190
	v_lshlrev_b32_e32 v92, 16, v191
	v_and_b32_e32 v93, 0xffff0000, v191
	v_lshlrev_b32_e32 v88, 16, v189
	v_and_b32_e32 v89, 0xffff0000, v189
	v_pk_mul_f32 v[82:83], v[84:85], v[82:83]
	v_pk_mul_f32 v[84:85], v[78:79], v[92:93]
	v_pk_mul_f32 v[78:79], v[76:77], v[90:91]
	v_add_u32_e32 v94, 0x30000, v81
	v_pk_mul_f32 v[86:87], v[86:87], v[88:89]
	v_cvt_pk_bf16_f32 v76, v82, v83
	s_nop 0
	v_cvt_pk_bf16_f32 v77, v86, v87
	v_cvt_pk_bf16_f32 v78, v78, v79
	v_cvt_pk_bf16_f32 v79, v84, v85
	global_store_dwordx4 v94, v[76:79], s[72:73]
	s_nop 1
	v_lshlrev_b32_e32 v76, 16, v16
	v_and_b32_e32 v77, 0xffff0000, v16
	v_lshlrev_b32_e32 v16, 16, v17
	v_and_b32_e32 v17, 0xffff0000, v17
	v_lshlrev_b32_e32 v78, 16, v18
	v_and_b32_e32 v79, 0xffff0000, v18
	v_lshlrev_b32_e32 v18, 16, v19
	v_and_b32_e32 v19, 0xffff0000, v19
	v_pk_mul_f32 v[74:75], v[74:75], v[16:17]
	v_pk_mul_f32 v[16:17], v[72:73], v[76:77]
	v_pk_mul_f32 v[70:71], v[70:71], v[18:19]
	v_pk_mul_f32 v[18:19], v[68:69], v[78:79]
	v_add_u32_e32 v68, 0x30100, v81
	v_cvt_pk_bf16_f32 v16, v16, v17
	v_cvt_pk_bf16_f32 v17, v74, v75
	v_cvt_pk_bf16_f32 v18, v18, v19
	v_cvt_pk_bf16_f32 v19, v70, v71
	global_store_dwordx4 v68, v[16:19], s[72:73]
	s_nop 1
	v_add_u32_e32 v16, 0x121a00, v80
	global_load_dwordx4 v[72:75], v16, s[68:69]
	v_add_u32_e32 v16, 0x121b00, v80
	global_load_dwordx4 v[76:79], v16, s[68:69]
	v_add_u32_e32 v16, 0x145a00, v80
	global_load_dwordx4 v[82:85], v16, s[68:69]
	v_add_u32_e32 v16, 0x145b00, v80
	global_load_dwordx4 v[86:89], v16, s[68:69]
	v_add_u32_e32 v16, 0x169a00, v80
	global_load_dwordx4 v[90:93], v16, s[68:69]
	v_add_u32_e32 v16, 0x169b00, v80
	global_load_dwordx4 v[94:97], v16, s[68:69]
	v_add_u32_e32 v16, 0x18da00, v80
	v_add_u32_e32 v17, 0x18db00, v80
	global_load_dwordx4 v[68:71], v16, s[68:69]
	s_nop 0
	global_load_dwordx4 v[16:19], v17, s[68:69]
	v_add_u32_e32 v80, 0x80000, v81
	s_waitcnt vmcnt(7)
	v_lshlrev_b32_e32 v98, 16, v72
	v_and_b32_e32 v99, 0xffff0000, v72
	v_lshlrev_b32_e32 v72, 16, v73
	v_and_b32_e32 v73, 0xffff0000, v73
	v_lshlrev_b32_e32 v100, 16, v74
	v_and_b32_e32 v101, 0xffff0000, v74
	v_lshlrev_b32_e32 v74, 16, v75
	v_and_b32_e32 v75, 0xffff0000, v75
	v_pk_mul_f32 v[62:63], v[62:63], v[72:73]
	v_pk_mul_f32 v[60:61], v[60:61], v[98:99]
	v_pk_mul_f32 v[66:67], v[66:67], v[74:75]
	v_pk_mul_f32 v[64:65], v[64:65], v[100:101]
	v_cvt_pk_bf16_f32 v60, v60, v61
	v_cvt_pk_bf16_f32 v61, v62, v63
	s_nop 0
	v_cvt_pk_bf16_f32 v62, v64, v65
	v_cvt_pk_bf16_f32 v63, v66, v67
	global_store_dwordx4 v80, v[60:63], s[72:73]
	s_waitcnt vmcnt(7)
	v_lshlrev_b32_e32 v64, 16, v78
	v_and_b32_e32 v65, 0xffff0000, v78
	v_lshlrev_b32_e32 v60, 16, v76
	v_and_b32_e32 v61, 0xffff0000, v76
	v_lshlrev_b32_e32 v62, 16, v77
	v_and_b32_e32 v63, 0xffff0000, v77
	v_lshlrev_b32_e32 v66, 16, v79
	v_and_b32_e32 v67, 0xffff0000, v79
	v_pk_mul_f32 v[54:55], v[54:55], v[62:63]
	v_pk_mul_f32 v[52:53], v[52:53], v[60:61]
	v_pk_mul_f32 v[56:57], v[56:57], v[64:65]
	v_pk_mul_f32 v[58:59], v[58:59], v[66:67]
	v_cvt_pk_bf16_f32 v52, v52, v53
	v_cvt_pk_bf16_f32 v53, v54, v55
	v_cvt_pk_bf16_f32 v54, v56, v57
	v_add_u32_e32 v56, 0x80100, v81
	v_cvt_pk_bf16_f32 v55, v58, v59
	global_store_dwordx4 v56, v[52:55], s[72:73]
	s_waitcnt vmcnt(7)
; __device__ __forceinline__ unsigned cvt_pk_bf16(float lo, float hi) { unsigned r; asm volatile("v_cvt_pk_bf16_f32 %0, %1, %2" : "=v"(r) : "v"(lo), "v"(hi)); return r; }
; __device__ __forceinline__ float bflo(unsigned w) { return __uint_as_float(w << 16); }
; __device__ __forceinline__ float bfhi(unsigned w) { return __uint_as_float(w & 0xffff0000u); }
; #define PG8_BAR __builtin_amdgcn_s_barrier()
;     __device__ __forceinline__ void scale(Acc& acc, const Unit& u, int wr, int wc, int fr, int fq, int pc, bool store) const {
;     ...
; #pragma unroll
;             for (int m = 0; m < 4; ++m) {
;                 const unsigned ooff = (unsigned)(row0 + ai * HALF + m * 16) * (unsigned)(ldo * 2) + (unsigned)col0 * 2u;
; #pragma unroll
;                 for (int bj = 0; bj < 2; ++bj) {
;                     const u32x4 gg = g[m][bj];
;                     const f32x4 s0 = (f32x4){bflo(gg.x), bfhi(gg.x), bflo(gg.y), bfhi(gg.y)}, s1 = (f32x4){bflo(gg.z), bfhi(gg.z), bflo(gg.w), bfhi(gg.w)};
;                     const f32x4 v0 = acc[ai][bj][m][0] * s0, v1 = acc[ai][bj][m][1] * s1;
;                     if (store) { u32x4 w; w.x = cvt_pk_bf16(v0[0], v0[1]); w.y = cvt_pk_bf16(v0[2], v0[3]); w.z = cvt_pk_bf16(v1[0], v1[1]); w.w = cvt_pk_bf16(v1[2], v1[3]); *(u32x4*)(Ob + (ooff + (unsigned)(bj * HALF * 2))) = w; }
;                     else { acc[ai][bj][m][0] = v0; acc[ai][bj][m][1] = v1; }
; template <class Epi, class Sched, bool ALIGN_EPI>
; __device__ __forceinline__ void gemm_phase(LAS unsigned char* lds, const Gemm g, const Sched& S, const Epi& E) {
;     ...
;         E(acc, cur, wr, wc, fr, fq);
;         if (!has_next) break;
; #pragma unroll
;         for (int a = 0; a < 2; ++a)
; #pragma unroll
;             for (int b = 0; b < 2; ++b)
; #pragma unroll
;                 for (int m = 0; m < 4; ++m)
; #pragma unroll
;                     for (int n = 0; n < 2; ++n) acc[a][b][m][n] = (f32x4){0.f, 0.f, 0.f, 0.f};
;         cur = nxt; cA = nA; cB = nB; ++ui;
;         if constexpr (ALIGN_EPI) { if (wr == 1) PG8_BAR; }
	v_lshlrev_b32_e32 v56, 16, v84
	v_and_b32_e32 v57, 0xffff0000, v84
	v_lshlrev_b32_e32 v52, 16, v82
	v_and_b32_e32 v53, 0xffff0000, v82
	v_lshlrev_b32_e32 v54, 16, v83
	v_and_b32_e32 v55, 0xffff0000, v83
	v_lshlrev_b32_e32 v58, 16, v85
	v_and_b32_e32 v59, 0xffff0000, v85
	v_pk_mul_f32 v[46:47], v[46:47], v[54:55]
	v_pk_mul_f32 v[44:45], v[44:45], v[52:53]
	v_add_u32_e32 v60, 0x90000, v81
	v_pk_mul_f32 v[50:51], v[50:51], v[58:59]
	v_pk_mul_f32 v[48:49], v[48:49], v[56:57]
	v_cvt_pk_bf16_f32 v44, v44, v45
	v_cvt_pk_bf16_f32 v45, v46, v47
	s_nop 0
	v_cvt_pk_bf16_f32 v46, v48, v49
	v_cvt_pk_bf16_f32 v47, v50, v51
	global_store_dwordx4 v60, v[44:47], s[72:73]
	s_waitcnt vmcnt(7)
	v_lshlrev_b32_e32 v48, 16, v88
	v_and_b32_e32 v49, 0xffff0000, v88
	v_lshlrev_b32_e32 v44, 16, v86
	v_and_b32_e32 v45, 0xffff0000, v86
	v_lshlrev_b32_e32 v46, 16, v87
	v_and_b32_e32 v47, 0xffff0000, v87
	v_lshlrev_b32_e32 v50, 16, v89
	v_and_b32_e32 v51, 0xffff0000, v89
	v_pk_mul_f32 v[38:39], v[38:39], v[46:47]
	v_pk_mul_f32 v[36:37], v[36:37], v[44:45]
	v_pk_mul_f32 v[40:41], v[40:41], v[48:49]
	v_pk_mul_f32 v[42:43], v[42:43], v[50:51]
	v_cvt_pk_bf16_f32 v36, v36, v37
	v_cvt_pk_bf16_f32 v37, v38, v39
	v_cvt_pk_bf16_f32 v38, v40, v41
	v_add_u32_e32 v40, 0x90100, v81
	v_cvt_pk_bf16_f32 v39, v42, v43
	global_store_dwordx4 v40, v[36:39], s[72:73]
	s_waitcnt vmcnt(7)
	v_lshlrev_b32_e32 v40, 16, v92
	v_and_b32_e32 v41, 0xffff0000, v92
	v_lshlrev_b32_e32 v36, 16, v90
	v_and_b32_e32 v37, 0xffff0000, v90
	v_lshlrev_b32_e32 v38, 16, v91
	v_and_b32_e32 v39, 0xffff0000, v91
	v_lshlrev_b32_e32 v42, 16, v93
	v_and_b32_e32 v43, 0xffff0000, v93
	v_pk_mul_f32 v[30:31], v[30:31], v[38:39]
	v_pk_mul_f32 v[28:29], v[28:29], v[36:37]
	v_add_u32_e32 v44, 0xa0000, v81
	v_pk_mul_f32 v[34:35], v[34:35], v[42:43]
	v_pk_mul_f32 v[32:33], v[32:33], v[40:41]
	v_cvt_pk_bf16_f32 v28, v28, v29
	v_cvt_pk_bf16_f32 v29, v30, v31
	s_nop 0
	v_cvt_pk_bf16_f32 v30, v32, v33
	v_cvt_pk_bf16_f32 v31, v34, v35
	global_store_dwordx4 v44, v[28:31], s[72:73]
	s_waitcnt vmcnt(7)
	v_lshlrev_b32_e32 v32, 16, v96
	v_and_b32_e32 v33, 0xffff0000, v96
	v_lshlrev_b32_e32 v28, 16, v94
	v_and_b32_e32 v29, 0xffff0000, v94
	v_lshlrev_b32_e32 v30, 16, v95
	v_and_b32_e32 v31, 0xffff0000, v95
	v_lshlrev_b32_e32 v34, 16, v97
	v_and_b32_e32 v35, 0xffff0000, v97
	v_pk_mul_f32 v[22:23], v[22:23], v[30:31]
	v_pk_mul_f32 v[20:21], v[20:21], v[28:29]
	v_pk_mul_f32 v[24:25], v[24:25], v[32:33]
	v_pk_mul_f32 v[26:27], v[26:27], v[34:35]
	v_cvt_pk_bf16_f32 v20, v20, v21
	v_cvt_pk_bf16_f32 v21, v22, v23
	v_cvt_pk_bf16_f32 v22, v24, v25
	v_add_u32_e32 v24, 0xa0100, v81
	v_cvt_pk_bf16_f32 v23, v26, v27
	global_store_dwordx4 v24, v[20:23], s[72:73]
	s_waitcnt vmcnt(7)
	v_lshlrev_b32_e32 v24, 16, v70
	v_and_b32_e32 v25, 0xffff0000, v70
	v_lshlrev_b32_e32 v20, 16, v68
	v_and_b32_e32 v21, 0xffff0000, v68
	v_lshlrev_b32_e32 v22, 16, v69
	v_and_b32_e32 v23, 0xffff0000, v69
	v_lshlrev_b32_e32 v26, 16, v71
	v_and_b32_e32 v27, 0xffff0000, v71
	v_add_u32_e32 v28, 0xb0000, v81
	v_pk_mul_f32 v[14:15], v[14:15], v[22:23]
	v_pk_mul_f32 v[12:13], v[12:13], v[20:21]
	v_pk_mul_f32 v[20:21], v[10:11], v[26:27]
	v_pk_mul_f32 v[10:11], v[8:9], v[24:25]
	v_cvt_pk_bf16_f32 v8, v12, v13
	v_cvt_pk_bf16_f32 v9, v14, v15
	s_waitcnt vmcnt(6)
	v_lshlrev_b32_e32 v12, 16, v18
	v_cvt_pk_bf16_f32 v10, v10, v11
	v_cvt_pk_bf16_f32 v11, v20, v21
	global_store_dwordx4 v28, v[8:11], s[72:73]
	v_and_b32_e32 v13, 0xffff0000, v18
	v_lshlrev_b32_e32 v14, 16, v19
	v_lshlrev_b32_e32 v8, 16, v16
	v_and_b32_e32 v9, 0xffff0000, v16
	v_and_b32_e32 v15, 0xffff0000, v19
	v_pk_mul_f32 v[4:5], v[4:5], v[8:9]
	v_lshlrev_b32_e32 v10, 16, v17
	v_and_b32_e32 v11, 0xffff0000, v17
	v_pk_mul_f32 v[8:9], v[2:3], v[14:15]
	v_pk_mul_f32 v[2:3], v[0:1], v[12:13]
	v_cvt_pk_bf16_f32 v0, v4, v5
	v_add_u32_e32 v4, 0xb0100, v81
	v_pk_mul_f32 v[6:7], v[6:7], v[10:11]
	s_nop 0
	v_cvt_pk_bf16_f32 v1, v6, v7
	v_cvt_pk_bf16_f32 v2, v2, v3
	v_cvt_pk_bf16_f32 v3, v8, v9
	global_store_dwordx4 v4, v[0:3], s[72:73]
	s_cbranch_vccnz .LBB0_1342
	s_andn2_b64 vcc, exec, s[4:5]
	s_cbranch_vccnz .LBB0_1341
	s_barrier
	s_branch .LBB0_1341
